# GEMM loops: k-inner pairs n-major with every second pair's K order reversed so the weight-fragment operand repeats across pair boundaries (accumulation order within a K-tile changes for half the accum
# speedup vs baseline: 1.0073x; 1.0073x over previous
.LBB0_178:
	s_add_u32 s26, s22, 0xfffc0080
	s_addc_u32 s27, s23, -1
	s_add_i32 s34, 0, 0x10000
	s_cmp_eq_u32 s59, 12
	s_cselect_b32 s31, s9, s27
	s_cselect_b32 s30, s15, s26
	s_cselect_b32 s27, s13, s58
	s_cselect_b32 s26, s56, s57
	s_add_i32 s35, 0, 0x14000
	v_add_u32_e32 v140, s34, v195
	v_add_u32_e32 v166, s35, v195
	ds_read_b128 v[128:131], v140
	ds_read_b128 v[132:135], v140 offset:1024
	ds_read_b128 v[136:139], v140 offset:2048
	ds_read_b128 v[140:143], v140 offset:3072
	ds_read_b128 v[144:147], v166
	ds_read_b128 v[148:151], v166 offset:1024
	ds_read_b128 v[180:183], v166 offset:2048
	ds_read_b128 v[184:187], v166 offset:3072
	s_add_i32 m0, s49, 0xc000
	ds_read_b128 v[188:191], v200
	ds_read_b128 v[202:205], v200 offset:1024
	ds_read_b128 v[206:209], v200 offset:2048
	ds_read_b128 v[210:213], v200 offset:3072
	ds_read_b128 v[228:231], v200 offset:4096
	ds_read_b128 v[232:235], v200 offset:5120
	ds_read_b128 v[236:239], v200 offset:6144
	ds_read_b128 v[240:243], v200 offset:7168
	global_load_lds_dwordx4 v160, s[22:23]
	s_add_i32 m0, s49, 0xe000
	s_nop 0
	global_load_lds_dwordx4 v162, s[22:23]
	s_waitcnt vmcnt(8)
	s_waitcnt lgkmcnt(0)
	s_barrier
	s_setprio 1
	s_waitcnt lgkmcnt(0)
	v_mfma_f32_16x16x32_bf16 v[124:127], v[128:131], v[188:191], v[124:127]
	v_mfma_f32_16x16x32_bf16 v[124:127], v[132:135], v[202:205], v[124:127]
	v_mfma_f32_16x16x32_bf16 v[112:115], v[132:135], v[210:213], v[112:115]
	v_mfma_f32_16x16x32_bf16 v[112:115], v[128:131], v[206:209], v[112:115]
	v_mfma_f32_16x16x32_bf16 v[96:99], v[128:131], v[228:231], v[96:99]
	v_mfma_f32_16x16x32_bf16 v[96:99], v[132:135], v[232:235], v[96:99]
	v_mfma_f32_16x16x32_bf16 v[80:83], v[132:135], v[240:243], v[80:83]
	v_mfma_f32_16x16x32_bf16 v[80:83], v[128:131], v[236:239], v[80:83]
	v_mfma_f32_16x16x32_bf16 v[120:123], v[136:139], v[188:191], v[120:123]
	v_mfma_f32_16x16x32_bf16 v[120:123], v[140:143], v[202:205], v[120:123]
	v_mfma_f32_16x16x32_bf16 v[104:107], v[140:143], v[210:213], v[104:107]
	v_mfma_f32_16x16x32_bf16 v[104:107], v[136:139], v[206:209], v[104:107]
	v_mfma_f32_16x16x32_bf16 v[88:91], v[136:139], v[228:231], v[88:91]
	v_mfma_f32_16x16x32_bf16 v[88:91], v[140:143], v[232:235], v[88:91]
	v_mfma_f32_16x16x32_bf16 v[72:75], v[140:143], v[240:243], v[72:75]
	v_mfma_f32_16x16x32_bf16 v[72:75], v[136:139], v[236:239], v[72:75]
	s_setprio 0
	s_setprio 1
	v_mfma_f32_16x16x32_bf16 v[116:119], v[144:147], v[188:191], v[116:119]
	v_mfma_f32_16x16x32_bf16 v[116:119], v[148:151], v[202:205], v[116:119]
	v_mfma_f32_16x16x32_bf16 v[100:103], v[148:151], v[210:213], v[100:103]
	v_mfma_f32_16x16x32_bf16 v[100:103], v[144:147], v[206:209], v[100:103]
	v_mfma_f32_16x16x32_bf16 v[84:87], v[144:147], v[228:231], v[84:87]
	v_mfma_f32_16x16x32_bf16 v[84:87], v[148:151], v[232:235], v[84:87]
	v_mfma_f32_16x16x32_bf16 v[68:71], v[148:151], v[240:243], v[68:71]
	v_mfma_f32_16x16x32_bf16 v[68:71], v[144:147], v[236:239], v[68:71]
	v_mfma_f32_16x16x32_bf16 v[108:111], v[180:183], v[188:191], v[108:111]
	v_mfma_f32_16x16x32_bf16 v[108:111], v[184:187], v[202:205], v[108:111]
	v_mfma_f32_16x16x32_bf16 v[92:95], v[184:187], v[210:213], v[92:95]
	v_mfma_f32_16x16x32_bf16 v[92:95], v[180:183], v[206:209], v[92:95]
	v_mfma_f32_16x16x32_bf16 v[76:79], v[180:183], v[228:231], v[76:79]
	v_mfma_f32_16x16x32_bf16 v[76:79], v[184:187], v[232:235], v[76:79]
	v_mfma_f32_16x16x32_bf16 v[64:67], v[184:187], v[240:243], v[64:67]
	v_mfma_f32_16x16x32_bf16 v[64:67], v[180:183], v[236:239], v[64:67]
	s_setprio 0
	s_barrier
	s_add_i32 s34, s34, s45
	s_add_u32 s98, s26, s20
	s_addc_u32 s99, s27, s21
	s_mov_b32 m0, s34
	ds_read_b128 v[188:191], v200 offset:16384
	ds_read_b128 v[202:205], v200 offset:17408
	ds_read_b128 v[206:209], v200 offset:18432
	ds_read_b128 v[210:213], v200 offset:19456
	ds_read_b128 v[228:231], v200 offset:20480
	ds_read_b128 v[232:235], v200 offset:21504
	ds_read_b128 v[236:239], v200 offset:22528
	ds_read_b128 v[240:243], v200 offset:23552
	global_load_lds_dwordx4 v168, s[26:27]
	s_add_i32 m0, s34, 0x2000
	s_add_u32 s36, s26, 0x40000
	s_addc_u32 s37, s27, 0
	s_add_i32 s34, s35, s45
	global_load_lds_dwordx4 v152, s[26:27]
	s_mov_b32 m0, s34
	s_nop 0
	global_load_lds_dwordx4 v168, s[36:37]
	s_add_i32 m0, s34, 0x2000
	s_nop 0
	global_load_lds_dwordx4 v152, s[36:37]
	s_add_u32 s100, s30, s20
	s_addc_u32 s101, s31, s21
	s_mov_b32 m0, s49
	s_nop 0
	global_load_lds_dwordx4 v156, s[30:31]
	s_mov_b32 m0, s50
	s_nop 0
	global_load_lds_dwordx4 v154, s[30:31]
	s_waitcnt vmcnt(8)
	s_waitcnt lgkmcnt(0)
	s_barrier
	s_setprio 1
	s_waitcnt lgkmcnt(0)
	v_mfma_f32_16x16x32_bf16 v[60:63], v[128:131], v[188:191], v[60:63]
	v_mfma_f32_16x16x32_bf16 v[60:63], v[132:135], v[202:205], v[60:63]
	v_mfma_f32_16x16x32_bf16 v[48:51], v[132:135], v[210:213], v[48:51]
	v_mfma_f32_16x16x32_bf16 v[48:51], v[128:131], v[206:209], v[48:51]
	v_mfma_f32_16x16x32_bf16 v[32:35], v[128:131], v[228:231], v[32:35]
	v_mfma_f32_16x16x32_bf16 v[32:35], v[132:135], v[232:235], v[32:35]
	v_mfma_f32_16x16x32_bf16 v[16:19], v[132:135], v[240:243], v[16:19]
	v_mfma_f32_16x16x32_bf16 v[16:19], v[128:131], v[236:239], v[16:19]
	v_mfma_f32_16x16x32_bf16 v[56:59], v[136:139], v[188:191], v[56:59]
	v_mfma_f32_16x16x32_bf16 v[56:59], v[140:143], v[202:205], v[56:59]
	v_mfma_f32_16x16x32_bf16 v[40:43], v[140:143], v[210:213], v[40:43]
	v_mfma_f32_16x16x32_bf16 v[40:43], v[136:139], v[206:209], v[40:43]
	v_mfma_f32_16x16x32_bf16 v[24:27], v[136:139], v[228:231], v[24:27]
	v_mfma_f32_16x16x32_bf16 v[24:27], v[140:143], v[232:235], v[24:27]
	v_mfma_f32_16x16x32_bf16 v[8:11], v[140:143], v[240:243], v[8:11]
	v_mfma_f32_16x16x32_bf16 v[8:11], v[136:139], v[236:239], v[8:11]
	s_setprio 0
	s_setprio 1
	v_mfma_f32_16x16x32_bf16 v[52:55], v[144:147], v[188:191], v[52:55]
	v_mfma_f32_16x16x32_bf16 v[52:55], v[148:151], v[202:205], v[52:55]
	v_mfma_f32_16x16x32_bf16 v[36:39], v[148:151], v[210:213], v[36:39]
	v_mfma_f32_16x16x32_bf16 v[36:39], v[144:147], v[206:209], v[36:39]
	v_mfma_f32_16x16x32_bf16 v[20:23], v[144:147], v[228:231], v[20:23]
	v_mfma_f32_16x16x32_bf16 v[20:23], v[148:151], v[232:235], v[20:23]
	v_mfma_f32_16x16x32_bf16 v[4:7], v[148:151], v[240:243], v[4:7]
	v_mfma_f32_16x16x32_bf16 v[4:7], v[144:147], v[236:239], v[4:7]
	v_mfma_f32_16x16x32_bf16 v[44:47], v[180:183], v[188:191], v[44:47]
	v_mfma_f32_16x16x32_bf16 v[44:47], v[184:187], v[202:205], v[44:47]
	v_mfma_f32_16x16x32_bf16 v[28:31], v[184:187], v[210:213], v[28:31]
	v_mfma_f32_16x16x32_bf16 v[28:31], v[180:183], v[206:209], v[28:31]
	v_mfma_f32_16x16x32_bf16 v[12:15], v[180:183], v[228:231], v[12:15]
	v_mfma_f32_16x16x32_bf16 v[12:15], v[184:187], v[232:235], v[12:15]
	v_mfma_f32_16x16x32_bf16 v[0:3], v[184:187], v[240:243], v[0:3]
	v_mfma_f32_16x16x32_bf16 v[0:3], v[180:183], v[236:239], v[0:3]
	s_setprio 0
	s_barrier
	s_add_i32 s34, 0, 0x18000
	s_add_i32 s35, 0, 0x1c000
	v_add_u32_e32 v140, s34, v195
	v_add_u32_e32 v184, s35, v195
	ds_read_b128 v[128:131], v140
	ds_read_b128 v[132:135], v140 offset:1024
	ds_read_b128 v[136:139], v140 offset:2048
	ds_read_b128 v[140:143], v140 offset:3072
	ds_read_b128 v[144:147], v184
	ds_read_b128 v[148:151], v184 offset:1024
	ds_read_b128 v[180:183], v184 offset:2048
	ds_read_b128 v[184:187], v184 offset:3072
	s_add_u32 s30, s30, 0x40000
	s_addc_u32 s31, s31, 0
	s_mov_b32 m0, s51
	ds_read_b128 v[188:191], v200 offset:32768
	ds_read_b128 v[202:205], v200 offset:33792
	ds_read_b128 v[206:209], v200 offset:34816
	ds_read_b128 v[210:213], v200 offset:35840
	ds_read_b128 v[228:231], v200 offset:36864
	ds_read_b128 v[232:235], v200 offset:37888
	ds_read_b128 v[236:239], v200 offset:38912
	ds_read_b128 v[240:243], v200 offset:39936
	global_load_lds_dwordx4 v156, s[30:31]
	s_mov_b32 m0, s52
	s_nop 0
	global_load_lds_dwordx4 v154, s[30:31]
	s_waitcnt vmcnt(8)
	s_waitcnt lgkmcnt(0)
	s_barrier
	s_setprio 1
	s_waitcnt lgkmcnt(0)
	v_mfma_f32_16x16x32_bf16 v[124:127], v[128:131], v[188:191], v[124:127]
	v_mfma_f32_16x16x32_bf16 v[124:127], v[132:135], v[202:205], v[124:127]
	v_mfma_f32_16x16x32_bf16 v[112:115], v[132:135], v[210:213], v[112:115]
	v_mfma_f32_16x16x32_bf16 v[112:115], v[128:131], v[206:209], v[112:115]
	v_mfma_f32_16x16x32_bf16 v[96:99], v[128:131], v[228:231], v[96:99]
	v_mfma_f32_16x16x32_bf16 v[96:99], v[132:135], v[232:235], v[96:99]
	v_mfma_f32_16x16x32_bf16 v[80:83], v[132:135], v[240:243], v[80:83]
	v_mfma_f32_16x16x32_bf16 v[80:83], v[128:131], v[236:239], v[80:83]
	v_mfma_f32_16x16x32_bf16 v[120:123], v[136:139], v[188:191], v[120:123]
	v_mfma_f32_16x16x32_bf16 v[120:123], v[140:143], v[202:205], v[120:123]
	v_mfma_f32_16x16x32_bf16 v[104:107], v[140:143], v[210:213], v[104:107]
	v_mfma_f32_16x16x32_bf16 v[104:107], v[136:139], v[206:209], v[104:107]
	v_mfma_f32_16x16x32_bf16 v[88:91], v[136:139], v[228:231], v[88:91]
	v_mfma_f32_16x16x32_bf16 v[88:91], v[140:143], v[232:235], v[88:91]
	v_mfma_f32_16x16x32_bf16 v[72:75], v[140:143], v[240:243], v[72:75]
	v_mfma_f32_16x16x32_bf16 v[72:75], v[136:139], v[236:239], v[72:75]
	s_setprio 0
	s_setprio 1
	v_mfma_f32_16x16x32_bf16 v[116:119], v[144:147], v[188:191], v[116:119]
	v_mfma_f32_16x16x32_bf16 v[116:119], v[148:151], v[202:205], v[116:119]
	v_mfma_f32_16x16x32_bf16 v[100:103], v[148:151], v[210:213], v[100:103]
	v_mfma_f32_16x16x32_bf16 v[100:103], v[144:147], v[206:209], v[100:103]
	v_mfma_f32_16x16x32_bf16 v[84:87], v[144:147], v[228:231], v[84:87]
	v_mfma_f32_16x16x32_bf16 v[84:87], v[148:151], v[232:235], v[84:87]
	v_mfma_f32_16x16x32_bf16 v[68:71], v[148:151], v[240:243], v[68:71]
	v_mfma_f32_16x16x32_bf16 v[68:71], v[144:147], v[236:239], v[68:71]
	v_mfma_f32_16x16x32_bf16 v[108:111], v[180:183], v[188:191], v[108:111]
	v_mfma_f32_16x16x32_bf16 v[108:111], v[184:187], v[202:205], v[108:111]
	v_mfma_f32_16x16x32_bf16 v[92:95], v[184:187], v[210:213], v[92:95]
	v_mfma_f32_16x16x32_bf16 v[92:95], v[180:183], v[206:209], v[92:95]
	v_mfma_f32_16x16x32_bf16 v[76:79], v[180:183], v[228:231], v[76:79]
	v_mfma_f32_16x16x32_bf16 v[76:79], v[184:187], v[232:235], v[76:79]
	v_mfma_f32_16x16x32_bf16 v[64:67], v[184:187], v[240:243], v[64:67]
	v_mfma_f32_16x16x32_bf16 v[64:67], v[180:183], v[236:239], v[64:67]
	s_setprio 0
	s_barrier
	s_add_i32 s30, s34, s45
	s_mov_b32 m0, s30
	ds_read_b128 v[188:191], v200 offset:49152
	ds_read_b128 v[202:205], v200 offset:50176
	ds_read_b128 v[206:209], v200 offset:51200
	ds_read_b128 v[210:213], v200 offset:52224
	ds_read_b128 v[228:231], v200 offset:53248
	ds_read_b128 v[232:235], v200 offset:54272
	ds_read_b128 v[236:239], v200 offset:55296
	ds_read_b128 v[240:243], v200 offset:56320
	global_load_lds_dwordx4 v168, s[98:99]
	s_add_i32 m0, s30, 0x2000
	s_add_u32 s26, s26, 0x40080
	s_addc_u32 s27, s27, 0
	s_add_i32 s30, s35, s45
	global_load_lds_dwordx4 v152, s[98:99]
	s_mov_b32 m0, s30
	s_nop 0
	global_load_lds_dwordx4 v168, s[26:27]
	s_add_i32 m0, s30, 0x2000
	s_nop 0
	global_load_lds_dwordx4 v152, s[26:27]
	s_mov_b32 m0, s24
	s_nop 0
	global_load_lds_dwordx4 v156, s[100:101]
	s_mov_b32 m0, s53
	s_nop 0
	global_load_lds_dwordx4 v154, s[100:101]
	s_waitcnt vmcnt(8)
	s_waitcnt lgkmcnt(0)
	s_barrier
	s_setprio 1
	s_waitcnt lgkmcnt(0)
	v_mfma_f32_16x16x32_bf16 v[60:63], v[128:131], v[188:191], v[60:63]
	v_mfma_f32_16x16x32_bf16 v[60:63], v[132:135], v[202:205], v[60:63]
	v_mfma_f32_16x16x32_bf16 v[48:51], v[132:135], v[210:213], v[48:51]
	v_mfma_f32_16x16x32_bf16 v[48:51], v[128:131], v[206:209], v[48:51]
	v_mfma_f32_16x16x32_bf16 v[32:35], v[128:131], v[228:231], v[32:35]
	v_mfma_f32_16x16x32_bf16 v[32:35], v[132:135], v[232:235], v[32:35]
	v_mfma_f32_16x16x32_bf16 v[16:19], v[132:135], v[240:243], v[16:19]
	v_mfma_f32_16x16x32_bf16 v[16:19], v[128:131], v[236:239], v[16:19]
	v_mfma_f32_16x16x32_bf16 v[56:59], v[136:139], v[188:191], v[56:59]
	v_mfma_f32_16x16x32_bf16 v[56:59], v[140:143], v[202:205], v[56:59]
	v_mfma_f32_16x16x32_bf16 v[40:43], v[140:143], v[210:213], v[40:43]
	v_mfma_f32_16x16x32_bf16 v[40:43], v[136:139], v[206:209], v[40:43]
	v_mfma_f32_16x16x32_bf16 v[24:27], v[136:139], v[228:231], v[24:27]
	v_mfma_f32_16x16x32_bf16 v[24:27], v[140:143], v[232:235], v[24:27]
	v_mfma_f32_16x16x32_bf16 v[8:11], v[140:143], v[240:243], v[8:11]
	v_mfma_f32_16x16x32_bf16 v[8:11], v[136:139], v[236:239], v[8:11]
	s_setprio 0
	s_setprio 1
	v_mfma_f32_16x16x32_bf16 v[52:55], v[144:147], v[188:191], v[52:55]
	v_mfma_f32_16x16x32_bf16 v[52:55], v[148:151], v[202:205], v[52:55]
	v_mfma_f32_16x16x32_bf16 v[36:39], v[148:151], v[210:213], v[36:39]
	v_mfma_f32_16x16x32_bf16 v[36:39], v[144:147], v[206:209], v[36:39]
	v_mfma_f32_16x16x32_bf16 v[20:23], v[144:147], v[228:231], v[20:23]
	v_mfma_f32_16x16x32_bf16 v[20:23], v[148:151], v[232:235], v[20:23]
	v_mfma_f32_16x16x32_bf16 v[4:7], v[148:151], v[240:243], v[4:7]
	v_mfma_f32_16x16x32_bf16 v[4:7], v[144:147], v[236:239], v[4:7]
	v_mfma_f32_16x16x32_bf16 v[44:47], v[180:183], v[188:191], v[44:47]
	v_mfma_f32_16x16x32_bf16 v[44:47], v[184:187], v[202:205], v[44:47]
	v_mfma_f32_16x16x32_bf16 v[28:31], v[184:187], v[210:213], v[28:31]
	v_mfma_f32_16x16x32_bf16 v[28:31], v[180:183], v[206:209], v[28:31]
	v_mfma_f32_16x16x32_bf16 v[12:15], v[180:183], v[228:231], v[12:15]
	v_mfma_f32_16x16x32_bf16 v[12:15], v[184:187], v[232:235], v[12:15]
	v_mfma_f32_16x16x32_bf16 v[0:3], v[184:187], v[240:243], v[0:3]
	v_mfma_f32_16x16x32_bf16 v[0:3], v[180:183], v[236:239], v[0:3]
	s_setprio 0
	s_barrier
	s_add_i32 s59, s59, 2
	s_add_u32 s22, s22, 0x100
	s_addc_u32 s23, s23, 0
	s_add_u32 s57, s57, 0x100
	s_addc_u32 s58, s58, 0
	s_cmp_gt_u32 s59, 13
	s_cbranch_scc0 .LBB0_178
	s_and_b64 vcc, exec, s[10:11]
	s_cbranch_vccz .LBB0_181
	s_barrier

.LBB0_776:
	s_add_u32 s26, s22, 0xfffc0080
	s_addc_u32 s27, s23, -1
	s_add_i32 s36, 0, 0x10000
	s_cmp_eq_u32 s55, 12
	s_cselect_b32 s31, s15, s27
	s_cselect_b32 s30, s51, s26
	s_cselect_b32 s27, s13, s54
	s_cselect_b32 s26, s52, s53
	s_add_i32 s56, 0, 0x14000
	v_add_u32_e32 v140, s36, v204
	v_add_u32_e32 v156, s56, v204
	ds_read_b128 v[128:131], v140
	ds_read_b128 v[132:135], v140 offset:1024
	ds_read_b128 v[136:139], v140 offset:2048
	ds_read_b128 v[140:143], v140 offset:3072
	ds_read_b128 v[144:147], v156
	ds_read_b128 v[148:151], v156 offset:1024
	ds_read_b128 v[152:155], v156 offset:2048
	ds_read_b128 v[156:159], v156 offset:3072
	s_add_i32 m0, s42, 0xc000
	ds_read_b128 v[182:185], v206
	ds_read_b128 v[186:189], v206 offset:1024
	ds_read_b128 v[190:193], v206 offset:2048
	ds_read_b128 v[194:197], v206 offset:3072
	ds_read_b128 v[198:201], v206 offset:4096
	ds_read_b128 v[208:211], v206 offset:5120
	ds_read_b128 v[212:215], v206 offset:6144
	ds_read_b128 v[228:231], v206 offset:7168
	global_load_lds_dwordx4 v166, s[22:23]
	s_add_i32 m0, s42, 0xe000
	s_nop 0
	global_load_lds_dwordx4 v180, s[22:23]
	s_waitcnt vmcnt(8)
	s_waitcnt lgkmcnt(0)
	s_barrier
	s_setprio 1
	s_waitcnt lgkmcnt(0)
	v_mfma_f32_16x16x32_bf16 v[124:127], v[128:131], v[182:185], v[124:127]
	v_mfma_f32_16x16x32_bf16 v[124:127], v[132:135], v[186:189], v[124:127]
	v_mfma_f32_16x16x32_bf16 v[108:111], v[132:135], v[194:197], v[108:111]
	v_mfma_f32_16x16x32_bf16 v[108:111], v[128:131], v[190:193], v[108:111]
	v_mfma_f32_16x16x32_bf16 v[92:95], v[128:131], v[198:201], v[92:95]
	v_mfma_f32_16x16x32_bf16 v[92:95], v[132:135], v[208:211], v[92:95]
	v_mfma_f32_16x16x32_bf16 v[76:79], v[132:135], v[228:231], v[76:79]
	v_mfma_f32_16x16x32_bf16 v[76:79], v[128:131], v[212:215], v[76:79]
	v_mfma_f32_16x16x32_bf16 v[120:123], v[136:139], v[182:185], v[120:123]
	v_mfma_f32_16x16x32_bf16 v[120:123], v[140:143], v[186:189], v[120:123]
	v_mfma_f32_16x16x32_bf16 v[104:107], v[140:143], v[194:197], v[104:107]
	v_mfma_f32_16x16x32_bf16 v[104:107], v[136:139], v[190:193], v[104:107]
	v_mfma_f32_16x16x32_bf16 v[88:91], v[136:139], v[198:201], v[88:91]
	v_mfma_f32_16x16x32_bf16 v[88:91], v[140:143], v[208:211], v[88:91]
	v_mfma_f32_16x16x32_bf16 v[72:75], v[140:143], v[228:231], v[72:75]
	v_mfma_f32_16x16x32_bf16 v[72:75], v[136:139], v[212:215], v[72:75]
	s_setprio 0
	s_setprio 1
	v_mfma_f32_16x16x32_bf16 v[116:119], v[144:147], v[182:185], v[116:119]
	v_mfma_f32_16x16x32_bf16 v[116:119], v[148:151], v[186:189], v[116:119]
	v_mfma_f32_16x16x32_bf16 v[100:103], v[148:151], v[194:197], v[100:103]
	v_mfma_f32_16x16x32_bf16 v[100:103], v[144:147], v[190:193], v[100:103]
	v_mfma_f32_16x16x32_bf16 v[84:87], v[144:147], v[198:201], v[84:87]
	v_mfma_f32_16x16x32_bf16 v[84:87], v[148:151], v[208:211], v[84:87]
	v_mfma_f32_16x16x32_bf16 v[68:71], v[148:151], v[228:231], v[68:71]
	v_mfma_f32_16x16x32_bf16 v[68:71], v[144:147], v[212:215], v[68:71]
	v_mfma_f32_16x16x32_bf16 v[112:115], v[152:155], v[182:185], v[112:115]
	v_mfma_f32_16x16x32_bf16 v[112:115], v[156:159], v[186:189], v[112:115]
	v_mfma_f32_16x16x32_bf16 v[96:99], v[156:159], v[194:197], v[96:99]
	v_mfma_f32_16x16x32_bf16 v[96:99], v[152:155], v[190:193], v[96:99]
	v_mfma_f32_16x16x32_bf16 v[80:83], v[152:155], v[198:201], v[80:83]
	v_mfma_f32_16x16x32_bf16 v[80:83], v[156:159], v[208:211], v[80:83]
	v_mfma_f32_16x16x32_bf16 v[64:67], v[156:159], v[228:231], v[64:67]
	v_mfma_f32_16x16x32_bf16 v[64:67], v[152:155], v[212:215], v[64:67]
	s_setprio 0
	s_barrier
	s_add_i32 s36, s36, s35
	s_add_u32 s98, s26, s20
	s_addc_u32 s99, s27, s21
	s_mov_b32 m0, s36
	ds_read_b128 v[182:185], v206 offset:16384
	ds_read_b128 v[186:189], v206 offset:17408
	ds_read_b128 v[190:193], v206 offset:18432
	ds_read_b128 v[194:197], v206 offset:19456
	ds_read_b128 v[198:201], v206 offset:20480
	ds_read_b128 v[208:211], v206 offset:21504
	ds_read_b128 v[212:215], v206 offset:22528
	ds_read_b128 v[228:231], v206 offset:23552
	global_load_lds_dwordx4 v168, s[26:27]
	s_add_i32 m0, s36, 0x2000
	s_add_u32 s36, s26, 0x40000
	s_addc_u32 s37, s27, 0
	s_add_i32 s56, s56, s35
	global_load_lds_dwordx4 v160, s[26:27]
	s_mov_b32 m0, s56
	s_nop 0
	global_load_lds_dwordx4 v168, s[36:37]
	s_add_i32 m0, s56, 0x2000
	s_nop 0
	global_load_lds_dwordx4 v160, s[36:37]
	s_add_u32 s100, s30, s20
	s_addc_u32 s101, s31, s21
	s_mov_b32 m0, s42
	s_nop 0
	global_load_lds_dwordx4 v164, s[30:31]
	s_mov_b32 m0, s43
	s_nop 0
	global_load_lds_dwordx4 v162, s[30:31]
	s_waitcnt vmcnt(8)
	s_waitcnt lgkmcnt(0)
	s_barrier
	s_setprio 1
	s_waitcnt lgkmcnt(0)
	v_mfma_f32_16x16x32_bf16 v[60:63], v[128:131], v[182:185], v[60:63]
	v_mfma_f32_16x16x32_bf16 v[60:63], v[132:135], v[186:189], v[60:63]
	v_mfma_f32_16x16x32_bf16 v[44:47], v[132:135], v[194:197], v[44:47]
	v_mfma_f32_16x16x32_bf16 v[44:47], v[128:131], v[190:193], v[44:47]
	v_mfma_f32_16x16x32_bf16 v[28:31], v[128:131], v[198:201], v[28:31]
	v_mfma_f32_16x16x32_bf16 v[28:31], v[132:135], v[208:211], v[28:31]
	v_mfma_f32_16x16x32_bf16 v[12:15], v[132:135], v[228:231], v[12:15]
	v_mfma_f32_16x16x32_bf16 v[12:15], v[128:131], v[212:215], v[12:15]
	v_mfma_f32_16x16x32_bf16 v[56:59], v[136:139], v[182:185], v[56:59]
	v_mfma_f32_16x16x32_bf16 v[56:59], v[140:143], v[186:189], v[56:59]
	v_mfma_f32_16x16x32_bf16 v[40:43], v[140:143], v[194:197], v[40:43]
	v_mfma_f32_16x16x32_bf16 v[40:43], v[136:139], v[190:193], v[40:43]
	v_mfma_f32_16x16x32_bf16 v[24:27], v[136:139], v[198:201], v[24:27]
	v_mfma_f32_16x16x32_bf16 v[24:27], v[140:143], v[208:211], v[24:27]
	v_mfma_f32_16x16x32_bf16 v[8:11], v[140:143], v[228:231], v[8:11]
	v_mfma_f32_16x16x32_bf16 v[8:11], v[136:139], v[212:215], v[8:11]
	s_setprio 0
	s_setprio 1
	v_mfma_f32_16x16x32_bf16 v[52:55], v[144:147], v[182:185], v[52:55]
	v_mfma_f32_16x16x32_bf16 v[52:55], v[148:151], v[186:189], v[52:55]
	v_mfma_f32_16x16x32_bf16 v[36:39], v[148:151], v[194:197], v[36:39]
	v_mfma_f32_16x16x32_bf16 v[36:39], v[144:147], v[190:193], v[36:39]
	v_mfma_f32_16x16x32_bf16 v[20:23], v[144:147], v[198:201], v[20:23]
	v_mfma_f32_16x16x32_bf16 v[20:23], v[148:151], v[208:211], v[20:23]
	v_mfma_f32_16x16x32_bf16 v[4:7], v[148:151], v[228:231], v[4:7]
	v_mfma_f32_16x16x32_bf16 v[4:7], v[144:147], v[212:215], v[4:7]
	v_mfma_f32_16x16x32_bf16 v[48:51], v[152:155], v[182:185], v[48:51]
	v_mfma_f32_16x16x32_bf16 v[48:51], v[156:159], v[186:189], v[48:51]
	v_mfma_f32_16x16x32_bf16 v[32:35], v[156:159], v[194:197], v[32:35]
	v_mfma_f32_16x16x32_bf16 v[32:35], v[152:155], v[190:193], v[32:35]
	v_mfma_f32_16x16x32_bf16 v[16:19], v[152:155], v[198:201], v[16:19]
	v_mfma_f32_16x16x32_bf16 v[16:19], v[156:159], v[208:211], v[16:19]
	v_mfma_f32_16x16x32_bf16 v[0:3], v[156:159], v[228:231], v[0:3]
	v_mfma_f32_16x16x32_bf16 v[0:3], v[152:155], v[212:215], v[0:3]
	s_setprio 0
	s_barrier
	s_add_i32 s36, 0, 0x18000
	s_add_i32 s37, 0, 0x1c000
	v_add_u32_e32 v140, s36, v204
	v_add_u32_e32 v156, s37, v204
	ds_read_b128 v[128:131], v140
	ds_read_b128 v[132:135], v140 offset:1024
	ds_read_b128 v[136:139], v140 offset:2048
	ds_read_b128 v[140:143], v140 offset:3072
	ds_read_b128 v[144:147], v156
	ds_read_b128 v[148:151], v156 offset:1024
	ds_read_b128 v[152:155], v156 offset:2048
	ds_read_b128 v[156:159], v156 offset:3072
	s_add_u32 s30, s30, 0x40000
	s_addc_u32 s31, s31, 0
	s_mov_b32 m0, s44
	ds_read_b128 v[182:185], v206 offset:32768
	ds_read_b128 v[186:189], v206 offset:33792
	ds_read_b128 v[190:193], v206 offset:34816
	ds_read_b128 v[194:197], v206 offset:35840
	ds_read_b128 v[198:201], v206 offset:36864
	ds_read_b128 v[208:211], v206 offset:37888
	ds_read_b128 v[212:215], v206 offset:38912
	ds_read_b128 v[228:231], v206 offset:39936
	global_load_lds_dwordx4 v164, s[30:31]
	s_mov_b32 m0, s45
	s_nop 0
	global_load_lds_dwordx4 v162, s[30:31]
	s_waitcnt vmcnt(8)
	s_waitcnt lgkmcnt(0)
	s_barrier
	s_setprio 1
	s_waitcnt lgkmcnt(0)
	v_mfma_f32_16x16x32_bf16 v[124:127], v[128:131], v[182:185], v[124:127]
	v_mfma_f32_16x16x32_bf16 v[124:127], v[132:135], v[186:189], v[124:127]
	v_mfma_f32_16x16x32_bf16 v[108:111], v[132:135], v[194:197], v[108:111]
	v_mfma_f32_16x16x32_bf16 v[108:111], v[128:131], v[190:193], v[108:111]
	v_mfma_f32_16x16x32_bf16 v[92:95], v[128:131], v[198:201], v[92:95]
	v_mfma_f32_16x16x32_bf16 v[92:95], v[132:135], v[208:211], v[92:95]
	v_mfma_f32_16x16x32_bf16 v[76:79], v[132:135], v[228:231], v[76:79]
	v_mfma_f32_16x16x32_bf16 v[76:79], v[128:131], v[212:215], v[76:79]
	v_mfma_f32_16x16x32_bf16 v[120:123], v[136:139], v[182:185], v[120:123]
	v_mfma_f32_16x16x32_bf16 v[120:123], v[140:143], v[186:189], v[120:123]
	v_mfma_f32_16x16x32_bf16 v[104:107], v[140:143], v[194:197], v[104:107]
	v_mfma_f32_16x16x32_bf16 v[104:107], v[136:139], v[190:193], v[104:107]
	v_mfma_f32_16x16x32_bf16 v[88:91], v[136:139], v[198:201], v[88:91]
	v_mfma_f32_16x16x32_bf16 v[88:91], v[140:143], v[208:211], v[88:91]
	v_mfma_f32_16x16x32_bf16 v[72:75], v[140:143], v[228:231], v[72:75]
	v_mfma_f32_16x16x32_bf16 v[72:75], v[136:139], v[212:215], v[72:75]
	s_setprio 0
	s_setprio 1
	v_mfma_f32_16x16x32_bf16 v[116:119], v[144:147], v[182:185], v[116:119]
	v_mfma_f32_16x16x32_bf16 v[116:119], v[148:151], v[186:189], v[116:119]
	v_mfma_f32_16x16x32_bf16 v[100:103], v[148:151], v[194:197], v[100:103]
	v_mfma_f32_16x16x32_bf16 v[100:103], v[144:147], v[190:193], v[100:103]
	v_mfma_f32_16x16x32_bf16 v[84:87], v[144:147], v[198:201], v[84:87]
	v_mfma_f32_16x16x32_bf16 v[84:87], v[148:151], v[208:211], v[84:87]
	v_mfma_f32_16x16x32_bf16 v[68:71], v[148:151], v[228:231], v[68:71]
	v_mfma_f32_16x16x32_bf16 v[68:71], v[144:147], v[212:215], v[68:71]
	v_mfma_f32_16x16x32_bf16 v[112:115], v[152:155], v[182:185], v[112:115]
	v_mfma_f32_16x16x32_bf16 v[112:115], v[156:159], v[186:189], v[112:115]
	v_mfma_f32_16x16x32_bf16 v[96:99], v[156:159], v[194:197], v[96:99]
	v_mfma_f32_16x16x32_bf16 v[96:99], v[152:155], v[190:193], v[96:99]
	v_mfma_f32_16x16x32_bf16 v[80:83], v[152:155], v[198:201], v[80:83]
	v_mfma_f32_16x16x32_bf16 v[80:83], v[156:159], v[208:211], v[80:83]
	v_mfma_f32_16x16x32_bf16 v[64:67], v[156:159], v[228:231], v[64:67]
	v_mfma_f32_16x16x32_bf16 v[64:67], v[152:155], v[212:215], v[64:67]
	s_setprio 0
	s_barrier
	s_add_i32 s30, s36, s35
	s_mov_b32 m0, s30
	ds_read_b128 v[182:185], v206 offset:49152
	ds_read_b128 v[186:189], v206 offset:50176
	ds_read_b128 v[190:193], v206 offset:51200
	ds_read_b128 v[194:197], v206 offset:52224
	ds_read_b128 v[198:201], v206 offset:53248
	ds_read_b128 v[208:211], v206 offset:54272
	ds_read_b128 v[212:215], v206 offset:55296
	ds_read_b128 v[228:231], v206 offset:56320
	global_load_lds_dwordx4 v168, s[98:99]
	s_add_i32 m0, s30, 0x2000
	s_add_u32 s26, s26, 0x40080
	s_addc_u32 s27, s27, 0
	s_add_i32 s30, s37, s35
	global_load_lds_dwordx4 v160, s[98:99]
	s_mov_b32 m0, s30
	s_nop 0
	global_load_lds_dwordx4 v168, s[26:27]
	s_add_i32 m0, s30, 0x2000
	s_nop 0
	global_load_lds_dwordx4 v160, s[26:27]
	s_mov_b32 m0, s47
	s_nop 0
	global_load_lds_dwordx4 v164, s[100:101]
	s_mov_b32 m0, s48
	s_nop 0
	global_load_lds_dwordx4 v162, s[100:101]
	s_waitcnt vmcnt(8)
	s_waitcnt lgkmcnt(0)
	s_barrier
	s_setprio 1
	s_waitcnt lgkmcnt(0)
	v_mfma_f32_16x16x32_bf16 v[60:63], v[128:131], v[182:185], v[60:63]
	v_mfma_f32_16x16x32_bf16 v[60:63], v[132:135], v[186:189], v[60:63]
	v_mfma_f32_16x16x32_bf16 v[44:47], v[132:135], v[194:197], v[44:47]
	v_mfma_f32_16x16x32_bf16 v[44:47], v[128:131], v[190:193], v[44:47]
	v_mfma_f32_16x16x32_bf16 v[28:31], v[128:131], v[198:201], v[28:31]
	v_mfma_f32_16x16x32_bf16 v[28:31], v[132:135], v[208:211], v[28:31]
	v_mfma_f32_16x16x32_bf16 v[12:15], v[132:135], v[228:231], v[12:15]
	v_mfma_f32_16x16x32_bf16 v[12:15], v[128:131], v[212:215], v[12:15]
	v_mfma_f32_16x16x32_bf16 v[56:59], v[136:139], v[182:185], v[56:59]
	v_mfma_f32_16x16x32_bf16 v[56:59], v[140:143], v[186:189], v[56:59]
	v_mfma_f32_16x16x32_bf16 v[40:43], v[140:143], v[194:197], v[40:43]
	v_mfma_f32_16x16x32_bf16 v[40:43], v[136:139], v[190:193], v[40:43]
	v_mfma_f32_16x16x32_bf16 v[24:27], v[136:139], v[198:201], v[24:27]
	v_mfma_f32_16x16x32_bf16 v[24:27], v[140:143], v[208:211], v[24:27]
	v_mfma_f32_16x16x32_bf16 v[8:11], v[140:143], v[228:231], v[8:11]
	v_mfma_f32_16x16x32_bf16 v[8:11], v[136:139], v[212:215], v[8:11]
	s_setprio 0
	s_setprio 1
	v_mfma_f32_16x16x32_bf16 v[52:55], v[144:147], v[182:185], v[52:55]
	v_mfma_f32_16x16x32_bf16 v[52:55], v[148:151], v[186:189], v[52:55]
	v_mfma_f32_16x16x32_bf16 v[36:39], v[148:151], v[194:197], v[36:39]
	v_mfma_f32_16x16x32_bf16 v[36:39], v[144:147], v[190:193], v[36:39]
	v_mfma_f32_16x16x32_bf16 v[20:23], v[144:147], v[198:201], v[20:23]
	v_mfma_f32_16x16x32_bf16 v[20:23], v[148:151], v[208:211], v[20:23]
	v_mfma_f32_16x16x32_bf16 v[4:7], v[148:151], v[228:231], v[4:7]
	v_mfma_f32_16x16x32_bf16 v[4:7], v[144:147], v[212:215], v[4:7]
	v_mfma_f32_16x16x32_bf16 v[48:51], v[152:155], v[182:185], v[48:51]
	v_mfma_f32_16x16x32_bf16 v[48:51], v[156:159], v[186:189], v[48:51]
	v_mfma_f32_16x16x32_bf16 v[32:35], v[156:159], v[194:197], v[32:35]
	v_mfma_f32_16x16x32_bf16 v[32:35], v[152:155], v[190:193], v[32:35]
	v_mfma_f32_16x16x32_bf16 v[16:19], v[152:155], v[198:201], v[16:19]
	v_mfma_f32_16x16x32_bf16 v[16:19], v[156:159], v[208:211], v[16:19]
	v_mfma_f32_16x16x32_bf16 v[0:3], v[156:159], v[228:231], v[0:3]
	v_mfma_f32_16x16x32_bf16 v[0:3], v[152:155], v[212:215], v[0:3]
	s_setprio 0
	s_barrier
	s_add_i32 s55, s55, 2
	s_add_u32 s22, s22, 0x100
	s_addc_u32 s23, s23, 0
	s_add_u32 s53, s53, 0x100
	s_addc_u32 s54, s54, 0
	s_cmp_gt_u32 s55, 13
	s_cbranch_scc0 .LBB0_776
	s_and_b64 vcc, exec, s[10:11]
	s_cbranch_vccz .LBB0_779
	s_barrier

.LBB0_890:
	s_add_u32 s18, s0, 0xfffc0080
	s_addc_u32 s19, s1, -1
	s_add_i32 s36, 0, 0x10000
	s_cmp_eq_u32 s50, 12
	s_cselect_b32 s23, s13, s19
	s_cselect_b32 s22, s46, s18
	s_cselect_b32 s19, s11, s49
	s_cselect_b32 s18, s47, s48
	s_add_i32 s51, 0, 0x14000
	v_add_u32_e32 v140, s36, v193
	v_add_u32_e32 v180, s51, v193
	ds_read_b128 v[128:131], v140
	ds_read_b128 v[132:135], v140 offset:1024
	ds_read_b128 v[136:139], v140 offset:2048
	ds_read_b128 v[140:143], v140 offset:3072
	ds_read_b128 v[144:147], v180
	ds_read_b128 v[148:151], v180 offset:1024
	ds_read_b128 v[164:167], v180 offset:2048
	ds_read_b128 v[180:183], v180 offset:3072
	s_add_i32 m0, s30, 0xc000
	ds_read_b128 v[184:187], v198
	ds_read_b128 v[188:191], v198 offset:1024
	ds_read_b128 v[200:203], v198 offset:2048
	ds_read_b128 v[204:207], v198 offset:3072
	ds_read_b128 v[208:211], v198 offset:4096
	ds_read_b128 v[212:215], v198 offset:5120
	ds_read_b128 v[228:231], v198 offset:6144
	ds_read_b128 v[232:235], v198 offset:7168
	global_load_lds_dwordx4 v160, s[0:1]
	s_add_i32 m0, s30, 0xe000
	s_nop 0
	global_load_lds_dwordx4 v162, s[0:1]
	s_waitcnt vmcnt(8)
	s_waitcnt lgkmcnt(0)
	s_barrier
	s_setprio 1
	s_waitcnt lgkmcnt(0)
	v_mfma_f32_16x16x32_bf16 v[124:127], v[128:131], v[184:187], v[124:127]
	v_mfma_f32_16x16x32_bf16 v[124:127], v[132:135], v[188:191], v[124:127]
	v_mfma_f32_16x16x32_bf16 v[108:111], v[132:135], v[204:207], v[108:111]
	v_mfma_f32_16x16x32_bf16 v[108:111], v[128:131], v[200:203], v[108:111]
	v_mfma_f32_16x16x32_bf16 v[92:95], v[128:131], v[208:211], v[92:95]
	v_mfma_f32_16x16x32_bf16 v[92:95], v[132:135], v[212:215], v[92:95]
	v_mfma_f32_16x16x32_bf16 v[76:79], v[132:135], v[232:235], v[76:79]
	v_mfma_f32_16x16x32_bf16 v[76:79], v[128:131], v[228:231], v[76:79]
	v_mfma_f32_16x16x32_bf16 v[120:123], v[136:139], v[184:187], v[120:123]
	v_mfma_f32_16x16x32_bf16 v[120:123], v[140:143], v[188:191], v[120:123]
	v_mfma_f32_16x16x32_bf16 v[104:107], v[140:143], v[204:207], v[104:107]
	v_mfma_f32_16x16x32_bf16 v[104:107], v[136:139], v[200:203], v[104:107]
	v_mfma_f32_16x16x32_bf16 v[88:91], v[136:139], v[208:211], v[88:91]
	v_mfma_f32_16x16x32_bf16 v[88:91], v[140:143], v[212:215], v[88:91]
	v_mfma_f32_16x16x32_bf16 v[72:75], v[140:143], v[232:235], v[72:75]
	v_mfma_f32_16x16x32_bf16 v[72:75], v[136:139], v[228:231], v[72:75]
	s_setprio 0
	s_setprio 1
	v_mfma_f32_16x16x32_bf16 v[116:119], v[144:147], v[184:187], v[116:119]
	v_mfma_f32_16x16x32_bf16 v[116:119], v[148:151], v[188:191], v[116:119]
	v_mfma_f32_16x16x32_bf16 v[100:103], v[148:151], v[204:207], v[100:103]
	v_mfma_f32_16x16x32_bf16 v[100:103], v[144:147], v[200:203], v[100:103]
	v_mfma_f32_16x16x32_bf16 v[84:87], v[144:147], v[208:211], v[84:87]
	v_mfma_f32_16x16x32_bf16 v[84:87], v[148:151], v[212:215], v[84:87]
	v_mfma_f32_16x16x32_bf16 v[68:71], v[148:151], v[232:235], v[68:71]
	v_mfma_f32_16x16x32_bf16 v[68:71], v[144:147], v[228:231], v[68:71]
	v_mfma_f32_16x16x32_bf16 v[112:115], v[164:167], v[184:187], v[112:115]
	v_mfma_f32_16x16x32_bf16 v[112:115], v[180:183], v[188:191], v[112:115]
	v_mfma_f32_16x16x32_bf16 v[96:99], v[180:183], v[204:207], v[96:99]
	v_mfma_f32_16x16x32_bf16 v[96:99], v[164:167], v[200:203], v[96:99]
	v_mfma_f32_16x16x32_bf16 v[80:83], v[164:167], v[208:211], v[80:83]
	v_mfma_f32_16x16x32_bf16 v[80:83], v[180:183], v[212:215], v[80:83]
	v_mfma_f32_16x16x32_bf16 v[64:67], v[180:183], v[232:235], v[64:67]
	v_mfma_f32_16x16x32_bf16 v[64:67], v[164:167], v[228:231], v[64:67]
	s_setprio 0
	s_barrier
	s_add_i32 s36, s36, s27
	s_add_u32 s98, s18, s20
	s_addc_u32 s99, s19, s21
	s_mov_b32 m0, s36
	ds_read_b128 v[184:187], v198 offset:16384
	ds_read_b128 v[188:191], v198 offset:17408
	ds_read_b128 v[200:203], v198 offset:18432
	ds_read_b128 v[204:207], v198 offset:19456
	ds_read_b128 v[208:211], v198 offset:20480
	ds_read_b128 v[212:215], v198 offset:21504
	ds_read_b128 v[228:231], v198 offset:22528
	ds_read_b128 v[232:235], v198 offset:23552
	global_load_lds_dwordx4 v168, s[18:19]
	s_add_i32 m0, s36, 0x2000
	s_add_u32 s36, s18, 0x40000
	s_addc_u32 s37, s19, 0
	s_add_i32 s51, s51, s27
	global_load_lds_dwordx4 v152, s[18:19]
	s_mov_b32 m0, s51
	s_nop 0
	global_load_lds_dwordx4 v168, s[36:37]
	s_add_i32 m0, s51, 0x2000
	s_nop 0
	global_load_lds_dwordx4 v152, s[36:37]
	s_add_u32 s100, s22, s20
	s_addc_u32 s101, s23, s21
	s_mov_b32 m0, s30
	s_nop 0
	global_load_lds_dwordx4 v156, s[22:23]
	s_mov_b32 m0, s31
	s_nop 0
	global_load_lds_dwordx4 v154, s[22:23]
	s_waitcnt vmcnt(8)
	s_waitcnt lgkmcnt(0)
	s_barrier
	s_setprio 1
	s_waitcnt lgkmcnt(0)
	v_mfma_f32_16x16x32_bf16 v[60:63], v[128:131], v[184:187], v[60:63]
	v_mfma_f32_16x16x32_bf16 v[60:63], v[132:135], v[188:191], v[60:63]
	v_mfma_f32_16x16x32_bf16 v[44:47], v[132:135], v[204:207], v[44:47]
	v_mfma_f32_16x16x32_bf16 v[44:47], v[128:131], v[200:203], v[44:47]
	v_mfma_f32_16x16x32_bf16 v[28:31], v[128:131], v[208:211], v[28:31]
	v_mfma_f32_16x16x32_bf16 v[28:31], v[132:135], v[212:215], v[28:31]
	v_mfma_f32_16x16x32_bf16 v[12:15], v[132:135], v[232:235], v[12:15]
	v_mfma_f32_16x16x32_bf16 v[12:15], v[128:131], v[228:231], v[12:15]
	v_mfma_f32_16x16x32_bf16 v[56:59], v[136:139], v[184:187], v[56:59]
	v_mfma_f32_16x16x32_bf16 v[56:59], v[140:143], v[188:191], v[56:59]
	v_mfma_f32_16x16x32_bf16 v[40:43], v[140:143], v[204:207], v[40:43]
	v_mfma_f32_16x16x32_bf16 v[40:43], v[136:139], v[200:203], v[40:43]
	v_mfma_f32_16x16x32_bf16 v[24:27], v[136:139], v[208:211], v[24:27]
	v_mfma_f32_16x16x32_bf16 v[24:27], v[140:143], v[212:215], v[24:27]
	v_mfma_f32_16x16x32_bf16 v[8:11], v[140:143], v[232:235], v[8:11]
	v_mfma_f32_16x16x32_bf16 v[8:11], v[136:139], v[228:231], v[8:11]
	s_setprio 0
	s_setprio 1
	v_mfma_f32_16x16x32_bf16 v[52:55], v[144:147], v[184:187], v[52:55]
	v_mfma_f32_16x16x32_bf16 v[52:55], v[148:151], v[188:191], v[52:55]
	v_mfma_f32_16x16x32_bf16 v[36:39], v[148:151], v[204:207], v[36:39]
	v_mfma_f32_16x16x32_bf16 v[36:39], v[144:147], v[200:203], v[36:39]
	v_mfma_f32_16x16x32_bf16 v[20:23], v[144:147], v[208:211], v[20:23]
	v_mfma_f32_16x16x32_bf16 v[20:23], v[148:151], v[212:215], v[20:23]
	v_mfma_f32_16x16x32_bf16 v[4:7], v[148:151], v[232:235], v[4:7]
	v_mfma_f32_16x16x32_bf16 v[4:7], v[144:147], v[228:231], v[4:7]
	v_mfma_f32_16x16x32_bf16 v[48:51], v[164:167], v[184:187], v[48:51]
	v_mfma_f32_16x16x32_bf16 v[48:51], v[180:183], v[188:191], v[48:51]
	v_mfma_f32_16x16x32_bf16 v[32:35], v[180:183], v[204:207], v[32:35]
	v_mfma_f32_16x16x32_bf16 v[32:35], v[164:167], v[200:203], v[32:35]
	v_mfma_f32_16x16x32_bf16 v[16:19], v[164:167], v[208:211], v[16:19]
	v_mfma_f32_16x16x32_bf16 v[16:19], v[180:183], v[212:215], v[16:19]
	v_mfma_f32_16x16x32_bf16 v[0:3], v[180:183], v[232:235], v[0:3]
	v_mfma_f32_16x16x32_bf16 v[0:3], v[164:167], v[228:231], v[0:3]
	s_setprio 0
	s_barrier
	s_add_i32 s36, 0, 0x18000
	s_add_i32 s37, 0, 0x1c000
	v_add_u32_e32 v140, s36, v193
	v_add_u32_e32 v180, s37, v193
	ds_read_b128 v[128:131], v140
	ds_read_b128 v[132:135], v140 offset:1024
	ds_read_b128 v[136:139], v140 offset:2048
	ds_read_b128 v[140:143], v140 offset:3072
	ds_read_b128 v[144:147], v180
	ds_read_b128 v[148:151], v180 offset:1024
	ds_read_b128 v[164:167], v180 offset:2048
	ds_read_b128 v[180:183], v180 offset:3072
	s_add_u32 s22, s22, 0x40000
	s_addc_u32 s23, s23, 0
	s_mov_b32 m0, s34
	ds_read_b128 v[184:187], v198 offset:32768
	ds_read_b128 v[188:191], v198 offset:33792
	ds_read_b128 v[200:203], v198 offset:34816
	ds_read_b128 v[204:207], v198 offset:35840
	ds_read_b128 v[208:211], v198 offset:36864
	ds_read_b128 v[212:215], v198 offset:37888
	ds_read_b128 v[228:231], v198 offset:38912
	ds_read_b128 v[232:235], v198 offset:39936
	global_load_lds_dwordx4 v156, s[22:23]
	s_mov_b32 m0, s35
	s_nop 0
	global_load_lds_dwordx4 v154, s[22:23]
	s_waitcnt vmcnt(8)
	s_waitcnt lgkmcnt(0)
	s_barrier
	s_setprio 1
	s_waitcnt lgkmcnt(0)
	v_mfma_f32_16x16x32_bf16 v[124:127], v[128:131], v[184:187], v[124:127]
	v_mfma_f32_16x16x32_bf16 v[124:127], v[132:135], v[188:191], v[124:127]
	v_mfma_f32_16x16x32_bf16 v[108:111], v[132:135], v[204:207], v[108:111]
	v_mfma_f32_16x16x32_bf16 v[108:111], v[128:131], v[200:203], v[108:111]
	v_mfma_f32_16x16x32_bf16 v[92:95], v[128:131], v[208:211], v[92:95]
	v_mfma_f32_16x16x32_bf16 v[92:95], v[132:135], v[212:215], v[92:95]
	v_mfma_f32_16x16x32_bf16 v[76:79], v[132:135], v[232:235], v[76:79]
	v_mfma_f32_16x16x32_bf16 v[76:79], v[128:131], v[228:231], v[76:79]
	v_mfma_f32_16x16x32_bf16 v[120:123], v[136:139], v[184:187], v[120:123]
	v_mfma_f32_16x16x32_bf16 v[120:123], v[140:143], v[188:191], v[120:123]
	v_mfma_f32_16x16x32_bf16 v[104:107], v[140:143], v[204:207], v[104:107]
	v_mfma_f32_16x16x32_bf16 v[104:107], v[136:139], v[200:203], v[104:107]
	v_mfma_f32_16x16x32_bf16 v[88:91], v[136:139], v[208:211], v[88:91]
	v_mfma_f32_16x16x32_bf16 v[88:91], v[140:143], v[212:215], v[88:91]
	v_mfma_f32_16x16x32_bf16 v[72:75], v[140:143], v[232:235], v[72:75]
	v_mfma_f32_16x16x32_bf16 v[72:75], v[136:139], v[228:231], v[72:75]
	s_setprio 0
	s_setprio 1
	v_mfma_f32_16x16x32_bf16 v[116:119], v[144:147], v[184:187], v[116:119]
	v_mfma_f32_16x16x32_bf16 v[116:119], v[148:151], v[188:191], v[116:119]
	v_mfma_f32_16x16x32_bf16 v[100:103], v[148:151], v[204:207], v[100:103]
	v_mfma_f32_16x16x32_bf16 v[100:103], v[144:147], v[200:203], v[100:103]
	v_mfma_f32_16x16x32_bf16 v[84:87], v[144:147], v[208:211], v[84:87]
	v_mfma_f32_16x16x32_bf16 v[84:87], v[148:151], v[212:215], v[84:87]
	v_mfma_f32_16x16x32_bf16 v[68:71], v[148:151], v[232:235], v[68:71]
	v_mfma_f32_16x16x32_bf16 v[68:71], v[144:147], v[228:231], v[68:71]
	v_mfma_f32_16x16x32_bf16 v[112:115], v[164:167], v[184:187], v[112:115]
	v_mfma_f32_16x16x32_bf16 v[112:115], v[180:183], v[188:191], v[112:115]
	v_mfma_f32_16x16x32_bf16 v[96:99], v[180:183], v[204:207], v[96:99]
	v_mfma_f32_16x16x32_bf16 v[96:99], v[164:167], v[200:203], v[96:99]
	v_mfma_f32_16x16x32_bf16 v[80:83], v[164:167], v[208:211], v[80:83]
	v_mfma_f32_16x16x32_bf16 v[80:83], v[180:183], v[212:215], v[80:83]
	v_mfma_f32_16x16x32_bf16 v[64:67], v[180:183], v[232:235], v[64:67]
	v_mfma_f32_16x16x32_bf16 v[64:67], v[164:167], v[228:231], v[64:67]
	s_setprio 0
	s_barrier
	s_add_i32 s22, s36, s27
	s_mov_b32 m0, s22
	ds_read_b128 v[184:187], v198 offset:49152
	ds_read_b128 v[188:191], v198 offset:50176
	ds_read_b128 v[200:203], v198 offset:51200
	ds_read_b128 v[204:207], v198 offset:52224
	ds_read_b128 v[208:211], v198 offset:53248
	ds_read_b128 v[212:215], v198 offset:54272
	ds_read_b128 v[228:231], v198 offset:55296
	ds_read_b128 v[232:235], v198 offset:56320
	global_load_lds_dwordx4 v168, s[98:99]
	s_add_i32 m0, s22, 0x2000
	s_add_u32 s18, s18, 0x40080
	s_addc_u32 s19, s19, 0
	s_add_i32 s22, s37, s27
	global_load_lds_dwordx4 v152, s[98:99]
	s_mov_b32 m0, s22
	s_nop 0
	global_load_lds_dwordx4 v168, s[18:19]
	s_add_i32 m0, s22, 0x2000
	s_nop 0
	global_load_lds_dwordx4 v152, s[18:19]
	s_mov_b32 m0, s24
	s_nop 0
	global_load_lds_dwordx4 v156, s[100:101]
	s_mov_b32 m0, s42
	s_nop 0
	global_load_lds_dwordx4 v154, s[100:101]
	s_waitcnt vmcnt(8)
	s_waitcnt lgkmcnt(0)
	s_barrier
	s_setprio 1
	s_waitcnt lgkmcnt(0)
	v_mfma_f32_16x16x32_bf16 v[60:63], v[128:131], v[184:187], v[60:63]
	v_mfma_f32_16x16x32_bf16 v[60:63], v[132:135], v[188:191], v[60:63]
	v_mfma_f32_16x16x32_bf16 v[44:47], v[132:135], v[204:207], v[44:47]
	v_mfma_f32_16x16x32_bf16 v[44:47], v[128:131], v[200:203], v[44:47]
	v_mfma_f32_16x16x32_bf16 v[28:31], v[128:131], v[208:211], v[28:31]
	v_mfma_f32_16x16x32_bf16 v[28:31], v[132:135], v[212:215], v[28:31]
	v_mfma_f32_16x16x32_bf16 v[12:15], v[132:135], v[232:235], v[12:15]
	v_mfma_f32_16x16x32_bf16 v[12:15], v[128:131], v[228:231], v[12:15]
	v_mfma_f32_16x16x32_bf16 v[56:59], v[136:139], v[184:187], v[56:59]
	v_mfma_f32_16x16x32_bf16 v[56:59], v[140:143], v[188:191], v[56:59]
	v_mfma_f32_16x16x32_bf16 v[40:43], v[140:143], v[204:207], v[40:43]
	v_mfma_f32_16x16x32_bf16 v[40:43], v[136:139], v[200:203], v[40:43]
	v_mfma_f32_16x16x32_bf16 v[24:27], v[136:139], v[208:211], v[24:27]
	v_mfma_f32_16x16x32_bf16 v[24:27], v[140:143], v[212:215], v[24:27]
	v_mfma_f32_16x16x32_bf16 v[8:11], v[140:143], v[232:235], v[8:11]
	v_mfma_f32_16x16x32_bf16 v[8:11], v[136:139], v[228:231], v[8:11]
	s_setprio 0
	s_setprio 1
	v_mfma_f32_16x16x32_bf16 v[52:55], v[144:147], v[184:187], v[52:55]
	v_mfma_f32_16x16x32_bf16 v[52:55], v[148:151], v[188:191], v[52:55]
	v_mfma_f32_16x16x32_bf16 v[36:39], v[148:151], v[204:207], v[36:39]
	v_mfma_f32_16x16x32_bf16 v[36:39], v[144:147], v[200:203], v[36:39]
	v_mfma_f32_16x16x32_bf16 v[20:23], v[144:147], v[208:211], v[20:23]
	v_mfma_f32_16x16x32_bf16 v[20:23], v[148:151], v[212:215], v[20:23]
	v_mfma_f32_16x16x32_bf16 v[4:7], v[148:151], v[232:235], v[4:7]
	v_mfma_f32_16x16x32_bf16 v[4:7], v[144:147], v[228:231], v[4:7]
	v_mfma_f32_16x16x32_bf16 v[48:51], v[164:167], v[184:187], v[48:51]
	v_mfma_f32_16x16x32_bf16 v[48:51], v[180:183], v[188:191], v[48:51]
	v_mfma_f32_16x16x32_bf16 v[32:35], v[180:183], v[204:207], v[32:35]
	v_mfma_f32_16x16x32_bf16 v[32:35], v[164:167], v[200:203], v[32:35]
	v_mfma_f32_16x16x32_bf16 v[16:19], v[164:167], v[208:211], v[16:19]
	v_mfma_f32_16x16x32_bf16 v[16:19], v[180:183], v[212:215], v[16:19]
	v_mfma_f32_16x16x32_bf16 v[0:3], v[180:183], v[232:235], v[0:3]
	v_mfma_f32_16x16x32_bf16 v[0:3], v[164:167], v[228:231], v[0:3]
	s_setprio 0
	s_barrier
	s_add_i32 s50, s50, 2
	s_add_u32 s0, s0, 0x100
	s_addc_u32 s1, s1, 0
	s_add_u32 s48, s48, 0x100
	s_addc_u32 s49, s49, 0
	s_cmp_gt_u32 s50, 13
	s_cbranch_scc0 .LBB0_890
	s_and_b64 vcc, exec, s[8:9]
	s_cbranch_vccz .LBB0_893
	s_barrier

.LBB0_986:
	s_add_u32 s34, s8, 0xfff00080
	s_addc_u32 s35, s9, -1
	s_add_i32 s36, 0, 0x10000
	s_cmp_eq_u32 s57, 60
	s_cselect_b32 s41, s23, s35
	s_cselect_b32 s40, s53, s34
	s_cselect_b32 s35, s19, s56
	s_cselect_b32 s34, s54, s55
	s_add_i32 s58, 0, 0x14000
	v_add_u32_e32 v140, s36, v228
	v_add_u32_e32 v156, s58, v228
	ds_read_b128 v[128:131], v140
	ds_read_b128 v[132:135], v140 offset:1024
	ds_read_b128 v[136:139], v140 offset:2048
	ds_read_b128 v[140:143], v140 offset:3072
	ds_read_b128 v[144:147], v156
	ds_read_b128 v[148:151], v156 offset:1024
	ds_read_b128 v[152:155], v156 offset:2048
	ds_read_b128 v[156:159], v156 offset:3072
	s_add_i32 m0, s44, 0xc000
	ds_read_b128 v[160:163], v230
	ds_read_b128 v[164:167], v230 offset:1024
	ds_read_b128 v[190:193], v230 offset:2048
	ds_read_b128 v[194:197], v230 offset:3072
	ds_read_b128 v[198:201], v230 offset:4096
	ds_read_b128 v[202:205], v230 offset:5120
	ds_read_b128 v[206:209], v230 offset:6144
	ds_read_b128 v[210:213], v230 offset:7168
	global_load_lds_dwordx4 v186, s[8:9]
	s_add_i32 m0, s44, 0xe000
	s_nop 0
	global_load_lds_dwordx4 v188, s[8:9]
	s_waitcnt vmcnt(8)
	s_waitcnt lgkmcnt(0)
	s_barrier
	s_setprio 1
	s_waitcnt lgkmcnt(0)
	v_mfma_f32_16x16x32_bf16 v[124:127], v[128:131], v[160:163], v[124:127]
	v_mfma_f32_16x16x32_bf16 v[124:127], v[132:135], v[164:167], v[124:127]
	v_mfma_f32_16x16x32_bf16 v[108:111], v[132:135], v[194:197], v[108:111]
	v_mfma_f32_16x16x32_bf16 v[108:111], v[128:131], v[190:193], v[108:111]
	v_mfma_f32_16x16x32_bf16 v[92:95], v[128:131], v[198:201], v[92:95]
	v_mfma_f32_16x16x32_bf16 v[92:95], v[132:135], v[202:205], v[92:95]
	v_mfma_f32_16x16x32_bf16 v[76:79], v[132:135], v[210:213], v[76:79]
	v_mfma_f32_16x16x32_bf16 v[76:79], v[128:131], v[206:209], v[76:79]
	v_mfma_f32_16x16x32_bf16 v[120:123], v[136:139], v[160:163], v[120:123]
	v_mfma_f32_16x16x32_bf16 v[120:123], v[140:143], v[164:167], v[120:123]
	v_mfma_f32_16x16x32_bf16 v[104:107], v[140:143], v[194:197], v[104:107]
	v_mfma_f32_16x16x32_bf16 v[104:107], v[136:139], v[190:193], v[104:107]
	v_mfma_f32_16x16x32_bf16 v[88:91], v[136:139], v[198:201], v[88:91]
	v_mfma_f32_16x16x32_bf16 v[88:91], v[140:143], v[202:205], v[88:91]
	v_mfma_f32_16x16x32_bf16 v[72:75], v[140:143], v[210:213], v[72:75]
	v_mfma_f32_16x16x32_bf16 v[72:75], v[136:139], v[206:209], v[72:75]
	s_setprio 0
	s_setprio 1
	v_mfma_f32_16x16x32_bf16 v[116:119], v[144:147], v[160:163], v[116:119]
	v_mfma_f32_16x16x32_bf16 v[116:119], v[148:151], v[164:167], v[116:119]
	v_mfma_f32_16x16x32_bf16 v[100:103], v[148:151], v[194:197], v[100:103]
	v_mfma_f32_16x16x32_bf16 v[100:103], v[144:147], v[190:193], v[100:103]
	v_mfma_f32_16x16x32_bf16 v[84:87], v[144:147], v[198:201], v[84:87]
	v_mfma_f32_16x16x32_bf16 v[84:87], v[148:151], v[202:205], v[84:87]
	v_mfma_f32_16x16x32_bf16 v[68:71], v[148:151], v[210:213], v[68:71]
	v_mfma_f32_16x16x32_bf16 v[68:71], v[144:147], v[206:209], v[68:71]
	v_mfma_f32_16x16x32_bf16 v[112:115], v[152:155], v[160:163], v[112:115]
	v_mfma_f32_16x16x32_bf16 v[112:115], v[156:159], v[164:167], v[112:115]
	v_mfma_f32_16x16x32_bf16 v[96:99], v[156:159], v[194:197], v[96:99]
	v_mfma_f32_16x16x32_bf16 v[96:99], v[152:155], v[190:193], v[96:99]
	v_mfma_f32_16x16x32_bf16 v[80:83], v[152:155], v[198:201], v[80:83]
	v_mfma_f32_16x16x32_bf16 v[80:83], v[156:159], v[202:205], v[80:83]
	v_mfma_f32_16x16x32_bf16 v[64:67], v[156:159], v[210:213], v[64:67]
	v_mfma_f32_16x16x32_bf16 v[64:67], v[152:155], v[206:209], v[64:67]
	s_setprio 0
	s_barrier
	s_add_i32 s36, s36, s43
	s_add_u32 s98, s34, s20
	s_addc_u32 s99, s35, s21
	s_mov_b32 m0, s36
	ds_read_b128 v[160:163], v230 offset:16384
	ds_read_b128 v[164:167], v230 offset:17408
	ds_read_b128 v[190:193], v230 offset:18432
	ds_read_b128 v[194:197], v230 offset:19456
	ds_read_b128 v[198:201], v230 offset:20480
	ds_read_b128 v[202:205], v230 offset:21504
	ds_read_b128 v[206:209], v230 offset:22528
	ds_read_b128 v[210:213], v230 offset:23552
	global_load_lds_dwordx4 v168, s[34:35]
	s_add_i32 m0, s36, 0x2000
	s_add_u32 s36, s34, 0x100000
	s_addc_u32 s37, s35, 0
	s_add_i32 s58, s58, s43
	global_load_lds_dwordx4 v180, s[34:35]
	s_mov_b32 m0, s58
	s_nop 0
	global_load_lds_dwordx4 v168, s[36:37]
	s_add_i32 m0, s58, 0x2000
	s_nop 0
	global_load_lds_dwordx4 v180, s[36:37]
	s_add_u32 s100, s40, s20
	s_addc_u32 s101, s41, s21
	s_mov_b32 m0, s44
	s_nop 0
	global_load_lds_dwordx4 v184, s[40:41]
	s_mov_b32 m0, s45
	s_nop 0
	global_load_lds_dwordx4 v182, s[40:41]
	s_waitcnt vmcnt(8)
	s_waitcnt lgkmcnt(0)
	s_barrier
	s_setprio 1
	s_waitcnt lgkmcnt(0)
	v_mfma_f32_16x16x32_bf16 v[60:63], v[128:131], v[160:163], v[60:63]
	v_mfma_f32_16x16x32_bf16 v[60:63], v[132:135], v[164:167], v[60:63]
	v_mfma_f32_16x16x32_bf16 v[44:47], v[132:135], v[194:197], v[44:47]
	v_mfma_f32_16x16x32_bf16 v[44:47], v[128:131], v[190:193], v[44:47]
	v_mfma_f32_16x16x32_bf16 v[28:31], v[128:131], v[198:201], v[28:31]
	v_mfma_f32_16x16x32_bf16 v[28:31], v[132:135], v[202:205], v[28:31]
	v_mfma_f32_16x16x32_bf16 v[12:15], v[132:135], v[210:213], v[12:15]
	v_mfma_f32_16x16x32_bf16 v[12:15], v[128:131], v[206:209], v[12:15]
	v_mfma_f32_16x16x32_bf16 v[56:59], v[136:139], v[160:163], v[56:59]
	v_mfma_f32_16x16x32_bf16 v[56:59], v[140:143], v[164:167], v[56:59]
	v_mfma_f32_16x16x32_bf16 v[40:43], v[140:143], v[194:197], v[40:43]
	v_mfma_f32_16x16x32_bf16 v[40:43], v[136:139], v[190:193], v[40:43]
	v_mfma_f32_16x16x32_bf16 v[24:27], v[136:139], v[198:201], v[24:27]
	v_mfma_f32_16x16x32_bf16 v[24:27], v[140:143], v[202:205], v[24:27]
	v_mfma_f32_16x16x32_bf16 v[8:11], v[140:143], v[210:213], v[8:11]
	v_mfma_f32_16x16x32_bf16 v[8:11], v[136:139], v[206:209], v[8:11]
	s_setprio 0
	s_setprio 1
	v_mfma_f32_16x16x32_bf16 v[52:55], v[144:147], v[160:163], v[52:55]
	v_mfma_f32_16x16x32_bf16 v[52:55], v[148:151], v[164:167], v[52:55]
	v_mfma_f32_16x16x32_bf16 v[36:39], v[148:151], v[194:197], v[36:39]
	v_mfma_f32_16x16x32_bf16 v[36:39], v[144:147], v[190:193], v[36:39]
	v_mfma_f32_16x16x32_bf16 v[20:23], v[144:147], v[198:201], v[20:23]
	v_mfma_f32_16x16x32_bf16 v[20:23], v[148:151], v[202:205], v[20:23]
	v_mfma_f32_16x16x32_bf16 v[4:7], v[148:151], v[210:213], v[4:7]
	v_mfma_f32_16x16x32_bf16 v[4:7], v[144:147], v[206:209], v[4:7]
	v_mfma_f32_16x16x32_bf16 v[48:51], v[152:155], v[160:163], v[48:51]
	v_mfma_f32_16x16x32_bf16 v[48:51], v[156:159], v[164:167], v[48:51]
	v_mfma_f32_16x16x32_bf16 v[32:35], v[156:159], v[194:197], v[32:35]
	v_mfma_f32_16x16x32_bf16 v[32:35], v[152:155], v[190:193], v[32:35]
	v_mfma_f32_16x16x32_bf16 v[16:19], v[152:155], v[198:201], v[16:19]
	v_mfma_f32_16x16x32_bf16 v[16:19], v[156:159], v[202:205], v[16:19]
	v_mfma_f32_16x16x32_bf16 v[0:3], v[156:159], v[210:213], v[0:3]
	v_mfma_f32_16x16x32_bf16 v[0:3], v[152:155], v[206:209], v[0:3]
	s_setprio 0
	s_barrier
	s_add_i32 s58, 0, 0x18000
	s_add_i32 s59, 0, 0x1c000
	v_add_u32_e32 v140, s58, v228
	v_add_u32_e32 v156, s59, v228
	ds_read_b128 v[128:131], v140
	ds_read_b128 v[132:135], v140 offset:1024
	ds_read_b128 v[136:139], v140 offset:2048
	ds_read_b128 v[140:143], v140 offset:3072
	ds_read_b128 v[144:147], v156
	ds_read_b128 v[148:151], v156 offset:1024
	ds_read_b128 v[152:155], v156 offset:2048
	ds_read_b128 v[156:159], v156 offset:3072
	s_add_u32 s36, s40, 0x100000
	s_addc_u32 s37, s41, 0
	s_mov_b32 m0, s46
	ds_read_b128 v[160:163], v230 offset:32768
	ds_read_b128 v[164:167], v230 offset:33792
	ds_read_b128 v[190:193], v230 offset:34816
	ds_read_b128 v[194:197], v230 offset:35840
	ds_read_b128 v[198:201], v230 offset:36864
	ds_read_b128 v[202:205], v230 offset:37888
	ds_read_b128 v[206:209], v230 offset:38912
	ds_read_b128 v[210:213], v230 offset:39936
	global_load_lds_dwordx4 v184, s[36:37]
	s_mov_b32 m0, s47
	s_nop 0
	global_load_lds_dwordx4 v182, s[36:37]
	s_waitcnt vmcnt(8)
	s_waitcnt lgkmcnt(0)
	s_barrier
	s_setprio 1
	s_waitcnt lgkmcnt(0)
	v_mfma_f32_16x16x32_bf16 v[124:127], v[128:131], v[160:163], v[124:127]
	v_mfma_f32_16x16x32_bf16 v[124:127], v[132:135], v[164:167], v[124:127]
	v_mfma_f32_16x16x32_bf16 v[108:111], v[132:135], v[194:197], v[108:111]
	v_mfma_f32_16x16x32_bf16 v[108:111], v[128:131], v[190:193], v[108:111]
	v_mfma_f32_16x16x32_bf16 v[92:95], v[128:131], v[198:201], v[92:95]
	v_mfma_f32_16x16x32_bf16 v[92:95], v[132:135], v[202:205], v[92:95]
	v_mfma_f32_16x16x32_bf16 v[76:79], v[132:135], v[210:213], v[76:79]
	v_mfma_f32_16x16x32_bf16 v[76:79], v[128:131], v[206:209], v[76:79]
	v_mfma_f32_16x16x32_bf16 v[120:123], v[136:139], v[160:163], v[120:123]
	v_mfma_f32_16x16x32_bf16 v[120:123], v[140:143], v[164:167], v[120:123]
	v_mfma_f32_16x16x32_bf16 v[104:107], v[140:143], v[194:197], v[104:107]
	v_mfma_f32_16x16x32_bf16 v[104:107], v[136:139], v[190:193], v[104:107]
	v_mfma_f32_16x16x32_bf16 v[88:91], v[136:139], v[198:201], v[88:91]
	v_mfma_f32_16x16x32_bf16 v[88:91], v[140:143], v[202:205], v[88:91]
	v_mfma_f32_16x16x32_bf16 v[72:75], v[140:143], v[210:213], v[72:75]
	v_mfma_f32_16x16x32_bf16 v[72:75], v[136:139], v[206:209], v[72:75]
	s_setprio 0
	s_setprio 1
	v_mfma_f32_16x16x32_bf16 v[116:119], v[144:147], v[160:163], v[116:119]
	v_mfma_f32_16x16x32_bf16 v[116:119], v[148:151], v[164:167], v[116:119]
	v_mfma_f32_16x16x32_bf16 v[100:103], v[148:151], v[194:197], v[100:103]
	v_mfma_f32_16x16x32_bf16 v[100:103], v[144:147], v[190:193], v[100:103]
	v_mfma_f32_16x16x32_bf16 v[84:87], v[144:147], v[198:201], v[84:87]
	v_mfma_f32_16x16x32_bf16 v[84:87], v[148:151], v[202:205], v[84:87]
	v_mfma_f32_16x16x32_bf16 v[68:71], v[148:151], v[210:213], v[68:71]
	v_mfma_f32_16x16x32_bf16 v[68:71], v[144:147], v[206:209], v[68:71]
	v_mfma_f32_16x16x32_bf16 v[112:115], v[152:155], v[160:163], v[112:115]
	v_mfma_f32_16x16x32_bf16 v[112:115], v[156:159], v[164:167], v[112:115]
	v_mfma_f32_16x16x32_bf16 v[96:99], v[156:159], v[194:197], v[96:99]
	v_mfma_f32_16x16x32_bf16 v[96:99], v[152:155], v[190:193], v[96:99]
	v_mfma_f32_16x16x32_bf16 v[80:83], v[152:155], v[198:201], v[80:83]
	v_mfma_f32_16x16x32_bf16 v[80:83], v[156:159], v[202:205], v[80:83]
	v_mfma_f32_16x16x32_bf16 v[64:67], v[156:159], v[210:213], v[64:67]
	v_mfma_f32_16x16x32_bf16 v[64:67], v[152:155], v[206:209], v[64:67]
	s_setprio 0
	s_barrier
	s_add_i32 s36, s58, s43
	s_mov_b32 m0, s36
	ds_read_b128 v[160:163], v230 offset:49152
	ds_read_b128 v[164:167], v230 offset:50176
	ds_read_b128 v[190:193], v230 offset:51200
	ds_read_b128 v[194:197], v230 offset:52224
	ds_read_b128 v[198:201], v230 offset:53248
	ds_read_b128 v[202:205], v230 offset:54272
	ds_read_b128 v[206:209], v230 offset:55296
	ds_read_b128 v[210:213], v230 offset:56320
	global_load_lds_dwordx4 v168, s[98:99]
	s_add_i32 m0, s36, 0x2000
	s_add_u32 s34, s34, 0x100080
	s_addc_u32 s35, s35, 0
	s_add_i32 s36, s59, s43
	global_load_lds_dwordx4 v180, s[98:99]
	s_mov_b32 m0, s36
	s_nop 0
	global_load_lds_dwordx4 v168, s[34:35]
	s_add_i32 m0, s36, 0x2000
	s_nop 0
	global_load_lds_dwordx4 v180, s[34:35]
	s_mov_b32 m0, s50
	s_nop 0
	global_load_lds_dwordx4 v184, s[100:101]
	s_mov_b32 m0, s51
	s_nop 0
	global_load_lds_dwordx4 v182, s[100:101]
	s_waitcnt vmcnt(8)
	s_waitcnt lgkmcnt(0)
	s_barrier
	s_setprio 1
	s_waitcnt lgkmcnt(0)
	v_mfma_f32_16x16x32_bf16 v[60:63], v[128:131], v[160:163], v[60:63]
	v_mfma_f32_16x16x32_bf16 v[60:63], v[132:135], v[164:167], v[60:63]
	v_mfma_f32_16x16x32_bf16 v[44:47], v[132:135], v[194:197], v[44:47]
	v_mfma_f32_16x16x32_bf16 v[44:47], v[128:131], v[190:193], v[44:47]
	v_mfma_f32_16x16x32_bf16 v[28:31], v[128:131], v[198:201], v[28:31]
	v_mfma_f32_16x16x32_bf16 v[28:31], v[132:135], v[202:205], v[28:31]
	v_mfma_f32_16x16x32_bf16 v[12:15], v[132:135], v[210:213], v[12:15]
	v_mfma_f32_16x16x32_bf16 v[12:15], v[128:131], v[206:209], v[12:15]
	v_mfma_f32_16x16x32_bf16 v[56:59], v[136:139], v[160:163], v[56:59]
	v_mfma_f32_16x16x32_bf16 v[56:59], v[140:143], v[164:167], v[56:59]
	v_mfma_f32_16x16x32_bf16 v[40:43], v[140:143], v[194:197], v[40:43]
	v_mfma_f32_16x16x32_bf16 v[40:43], v[136:139], v[190:193], v[40:43]
	v_mfma_f32_16x16x32_bf16 v[24:27], v[136:139], v[198:201], v[24:27]
	v_mfma_f32_16x16x32_bf16 v[24:27], v[140:143], v[202:205], v[24:27]
	v_mfma_f32_16x16x32_bf16 v[8:11], v[140:143], v[210:213], v[8:11]
	v_mfma_f32_16x16x32_bf16 v[8:11], v[136:139], v[206:209], v[8:11]
	s_setprio 0
	s_setprio 1
	v_mfma_f32_16x16x32_bf16 v[52:55], v[144:147], v[160:163], v[52:55]
	v_mfma_f32_16x16x32_bf16 v[52:55], v[148:151], v[164:167], v[52:55]
	v_mfma_f32_16x16x32_bf16 v[36:39], v[148:151], v[194:197], v[36:39]
	v_mfma_f32_16x16x32_bf16 v[36:39], v[144:147], v[190:193], v[36:39]
	v_mfma_f32_16x16x32_bf16 v[20:23], v[144:147], v[198:201], v[20:23]
	v_mfma_f32_16x16x32_bf16 v[20:23], v[148:151], v[202:205], v[20:23]
	v_mfma_f32_16x16x32_bf16 v[4:7], v[148:151], v[210:213], v[4:7]
	v_mfma_f32_16x16x32_bf16 v[4:7], v[144:147], v[206:209], v[4:7]
	v_mfma_f32_16x16x32_bf16 v[48:51], v[152:155], v[160:163], v[48:51]
	v_mfma_f32_16x16x32_bf16 v[48:51], v[156:159], v[164:167], v[48:51]
	v_mfma_f32_16x16x32_bf16 v[32:35], v[156:159], v[194:197], v[32:35]
	v_mfma_f32_16x16x32_bf16 v[32:35], v[152:155], v[190:193], v[32:35]
	v_mfma_f32_16x16x32_bf16 v[16:19], v[152:155], v[198:201], v[16:19]
	v_mfma_f32_16x16x32_bf16 v[16:19], v[156:159], v[202:205], v[16:19]
	v_mfma_f32_16x16x32_bf16 v[0:3], v[156:159], v[210:213], v[0:3]
	v_mfma_f32_16x16x32_bf16 v[0:3], v[152:155], v[206:209], v[0:3]
	s_setprio 0
	s_barrier
	s_add_i32 s57, s57, 2
	s_add_u32 s8, s8, 0x100
	s_addc_u32 s9, s9, 0
	s_add_u32 s55, s55, 0x100
	s_addc_u32 s56, s56, 0
	s_cmp_gt_u32 s57, 61
	s_cbranch_scc0 .LBB0_986
	s_and_b64 vcc, exec, s[12:13]
	s_cbranch_vccz .LBB0_989
	s_barrier
